# norm phases: dead first-row register copies and their vmcnt waits removed from the prologue, so the first row's parameter/partial loads issue without waiting for the first x row
# baseline (speedup 1.0000x reference)
; __device__ __forceinline__ int fresh_tid() { int t = threadIdx.x; asm volatile("" : "+v"(t)); return t; }
; #define NORM_LOADX(dst, r_) do { const int r__ = (r_); const float* xr_ = r__ < NLAT ? xlat + (size_t)r__ * DM : xctx + (size_t)(r__ - NLAT) * DM; \
;         _Pragma("unroll") for (int j = 0; j < 4; ++j) dst[j] = *(const f32x4*)(xr_ + 4 * lane + 256 * j); } while (0)
; __device__ __forceinline__ void norm_phase(const float* xlat, const float* xctx, const float* gvec, const float* mod, int sh_off, int sc_off, bf16_t* H, int nrows,
;                                            const float* part, const float* pgate, float* xctx_out, int row_lo) {
;     const int tid = fresh_tid(), lane = tid & 63, gw = row_lo + blockIdx.x * 8 + (tid >> 6), NGW = gridDim.x * 8;
;     f32x4 vn[4];
;     ...
;     if (gw < nrows) NORM_LOADX(vn, gw);
;     for (int row = gw; row < nrows; row += NGW) {
;         const int bb = row < NLAT ? row >> 11 : 8;
;         f32x4 v[4]; float ss = 0.f;
; #pragma unroll
;         for (int j = 0; j < 4; ++j) v[j] = vn[j];
;         if (row + NGW < nrows) NORM_LOADX(vn, row + NGW);
;         const float* mp = mod + bb * 6144;
;         f32x4 gg[4], sc[4], sh[4];
; #pragma unroll
;         for (int j = 0; j < 4; ++j) { const int col = 4 * lane + 256 * j; gg[j] = *(const f32x4*)(gvec + col); sc[j] = *(const f32x4*)(mp + sc_off + col); sh[j] = *(const f32x4*)(mp + sh_off + col); }
.LBB0_173:
	s_mul_i32 s0, s72, 0x36000
	v_readlane_b32 s1, v253, 20
	s_add_u32 s48, s1, s0
	v_readlane_b32 s0, v253, 21
	s_addc_u32 s49, s0, 0
	v_readlane_b32 s8, v252, 0
	v_readlane_b32 s52, v252, 16
	v_writelane_b32 v255, s6, 26
	s_and_b64 s[0:1], s[6:7], exec
	v_readlane_b32 s10, v252, 2
	v_readlane_b32 s11, v252, 3
	v_readlane_b32 s53, v252, 17
	v_writelane_b32 v255, s7, 27
	s_cselect_b32 s1, s53, s11
	s_cselect_b32 s0, s52, s10
	v_readlane_b32 s57, v252, 21
	v_writelane_b32 v255, s0, 28
	v_readlane_b32 s56, v252, 20
	v_readlane_b32 s58, v252, 22
	v_writelane_b32 v255, s1, 29
	s_cselect_b32 s0, s57, s27
	v_writelane_b32 v255, s0, 30
	s_cselect_b32 s0, s56, s26
	v_writelane_b32 v255, s0, 31
	v_readlane_b32 s0, v253, 22
	v_readlane_b32 s1, v253, 23
	s_lshl_b32 s58, s72, 10
	s_and_b64 s[6:7], s[0:1], s[4:5]
	s_and_b64 s[0:1], s[6:7], exec
	s_cselect_b32 s0, 0x4000, 0
	v_mov_b32_e32 v19, v192
	v_readlane_b32 s1, v253, 0
	s_add_i32 s1, s0, s1
	v_ashrrev_i32_e32 v18, 6, v19
	v_readlane_b32 s59, v252, 23
	v_add_u32_e32 v16, s1, v18
	s_movk_i32 s1, 0x4800
	v_readlane_b32 s9, v252, 1
	s_mov_b32 s59, s43
	v_cmp_gt_i32_e32 vcc, s1, v16
	v_readlane_b32 s12, v252, 4
	v_readlane_b32 s13, v252, 5
	v_readlane_b32 s14, v252, 6
	v_readlane_b32 s15, v252, 7
	v_readlane_b32 s54, v252, 18
	v_readlane_b32 s55, v252, 19
	v_readlane_b32 s60, v252, 24
	v_readlane_b32 s61, v252, 25
	v_readlane_b32 s62, v252, 26
	v_readlane_b32 s63, v252, 27
	v_readlane_b32 s64, v252, 28
	v_readlane_b32 s65, v252, 29
	v_readlane_b32 s66, v252, 30
	v_readlane_b32 s67, v252, 31
	s_and_saveexec_b64 s[8:9], vcc
	s_cbranch_execz .LBB0_180
	s_movk_i32 s1, 0x4000
	v_readlane_b32 s10, v255, 28
	v_cmp_gt_i32_e32 vcc, s1, v16
	v_readlane_b32 s1, v255, 30
	v_readlane_b32 s11, v255, 29
	v_add_u32_e32 v0, 0xffffc000, v16
	v_ashrrev_i32_e32 v17, 31, v16
	v_mov_b32_e32 v2, s1
	v_mov_b32_e32 v3, s11
	v_readlane_b32 s1, v255, 31
	v_cndmask_b32_e32 v1, 0, v17, vcc
	v_cndmask_b32_e32 v0, v0, v16, vcc
	v_cndmask_b32_e32 v3, v2, v3, vcc
	v_mov_b32_e32 v2, s1
	v_mov_b32_e32 v4, s10
	v_cndmask_b32_e32 v2, v2, v4, vcc
	v_lshlrev_b64 v[0:1], 12, v[0:1]
	v_lshl_add_u64 v[0:1], v[2:3], 0, v[0:1]
	v_lshlrev_b32_e32 v2, 2, v19
	v_and_b32_e32 v80, 0xfc, v2
	v_lshlrev_b32_e32 v160, 2, v80
	v_lshl_add_u64 v[0:1], v[0:1], 0, v[160:161]
	global_load_dwordx4 v[12:15], v[0:1], off
	global_load_dwordx4 v[8:11], v[0:1], off offset:1024
	global_load_dwordx4 v[4:7], v[0:1], off offset:2048
	s_nop 0
	global_load_dwordx4 v[0:3], v[0:1], off offset:3072
	v_readlane_b32 s12, v253, 18
	s_mov_b32 s14, s72
	v_readlane_b32 s64, v252, 16
	s_and_b64 s[10:11], s[4:5], exec
	v_readlane_b32 s13, v253, 19
	v_readlane_b32 s65, v252, 17
	v_readlane_b32 s66, v252, 18
	v_readlane_b32 s67, v252, 19
	v_readlane_b32 s76, v252, 28
	v_readlane_b32 s77, v252, 29
	s_cselect_b32 s1, s13, 0
	s_cselect_b32 s20, s12, 0
	s_lshl_b64 s[12:13], s[58:59], 2
	v_readlane_b32 s72, v252, 24
	v_readlane_b32 s78, v252, 30
	v_readlane_b32 s79, v252, 31
	s_mov_b64 s[64:65], s[76:77]
	s_mov_b32 s72, s14
	s_add_u32 s12, s64, s12
	v_readlane_b32 s14, v253, 26
	v_xor_b32_e32 v20, 1, v197
	s_addc_u32 s13, s65, s13
	v_readlane_b32 s15, v253, 27
	v_cmp_lt_i32_e32 vcc, v20, v207
	v_xor_b32_e32 v21, 2, v197
	v_lshl_add_u64 v[82:83], s[14:15], 0, v[160:161]
	s_add_u32 s14, s20, 0x800000
	v_cndmask_b32_e32 v20, v197, v20, vcc
	v_cmp_lt_i32_e32 vcc, v21, v207
	v_xor_b32_e32 v22, 4, v197
	s_addc_u32 s15, s1, 0
	v_cndmask_b32_e32 v21, v197, v21, vcc
	v_cmp_lt_i32_e32 vcc, v22, v207
	v_xor_b32_e32 v23, 8, v197
	s_add_u32 s46, s20, 0x1000000
	v_cndmask_b32_e32 v22, v197, v22, vcc
	v_cmp_lt_i32_e32 vcc, v23, v207
	v_xor_b32_e32 v24, 16, v197
	s_mov_b64 s[66:67], s[78:79]
	s_addc_u32 s47, s1, 0
	v_cndmask_b32_e32 v23, v197, v23, vcc
	v_cmp_lt_i32_e32 vcc, v24, v207
	s_add_u32 s66, s20, 0x1800000
	v_and_b32_e32 v19, 63, v19
	v_cndmask_b32_e32 v24, v197, v24, vcc
	v_cmp_lt_i32_e32 vcc, v204, v207
	v_lshlrev_b64 v[16:17], 11, v[16:17]
	v_lshl_add_u64 v[92:93], s[12:13], 0, v[160:161]
	s_addc_u32 s67, s1, 0
	v_readlane_b32 s1, v255, 13
	v_readlane_b32 s12, v255, 14
	v_cndmask_b32_e32 v25, v197, v204, vcc
	v_lshlrev_b32_e32 v81, 2, v20
	v_lshlrev_b32_e32 v99, 2, v22
	v_lshlrev_b32_e32 v101, 2, v24
	v_or_b32_e32 v20, 0x100, v80
	v_or_b32_e32 v22, 0x200, v80
	v_or_b32_e32 v24, 0x300, v80
	v_lshl_or_b32 v16, v19, 3, v16
	s_add_i32 s1, s1, s0
	s_add_i32 s0, s12, s0
	v_lshlrev_b32_e32 v98, 2, v21
	v_lshlrev_b32_e32 v100, 2, v23
	v_lshlrev_b32_e32 v102, 2, v25
	v_lshl_add_u64 v[84:85], s[18:19], 0, v[16:17]
	v_lshlrev_b32_e32 v86, 2, v20
	v_lshlrev_b32_e32 v88, 2, v22
	v_lshlrev_b32_e32 v90, 2, v24
	v_add_u32_e32 v96, s1, v18
	v_add_u32_e32 v94, s0, v18
	s_mov_b64 s[10:11], 0
	v_lshlrev_b32_e32 v160, 2, v80
	v_ashrrev_i32_e32 v95, 31, v94
	v_readlane_b32 s68, v252, 20
	v_readlane_b32 s69, v252, 21
	v_readlane_b32 s70, v252, 22
	s_nop 0
	s_nop 0
	s_nop 0
	s_nop 0
	s_nop 0
	s_nop 0
	s_nop 0
	s_nop 0
	s_nop 0
	s_nop 0
	s_nop 0
	s_nop 0
	v_readlane_b32 s71, v252, 23
	v_readlane_b32 s73, v252, 25
	v_readlane_b32 s74, v252, 26
	v_readlane_b32 s75, v252, 27
	s_branch .LBB0_176
; __device__ __forceinline__ u32x2 pack4(f32x4 v) { u32x2 w; w.x = cvt_pk_bf16(v[0], v[1]); w.y = cvt_pk_bf16(v[2], v[3]); return w; }
; __device__ __forceinline__ float wave_sum(float v) {
; #pragma unroll
;     for (int o = 1; o < 64; o <<= 1) v += __shfl_xor(v, o);
;     return v;
; __device__ __forceinline__ void norm_phase(const float* xlat, const float* xctx, const float* gvec, const float* mod, int sh_off, int sc_off, bf16_t* H, int nrows,
;                                            const float* part, const float* pgate, float* xctx_out, int row_lo) {
;     ...
;         for (int j = 0; j < 4; ++j) ss += (v[j][0] * v[j][0] + v[j][1] * v[j][1]) + (v[j][2] * v[j][2] + v[j][3] * v[j][3]);
;         const float rstd = __builtin_amdgcn_rsqf(wave_sum(ss) * (1.f / DM) + EPSV);
; #pragma unroll
;         for (int j = 0; j < 4; ++j) {
;             const int col = 4 * lane + 256 * j;
;             const f32x4 y = (v[j] * rstd) * gg[j];
;             const f32x4 hv = y * (sc[j] + 1.f) + sh[j];
;             *(u32x2*)(H + (size_t)row * DM + col) = pack4(hv);
;         }
.LBB0_175:
	s_or_b64 exec, exec, s[0:1]
	s_waitcnt vmcnt(16)
	v_pk_mul_f32 v[106:107], v[14:15], v[14:15]
	v_pk_mul_f32 v[108:109], v[12:13], v[12:13]
	v_pk_mul_f32 v[96:97], v[10:11], v[10:11]
	v_pk_mul_f32 v[104:105], v[8:9], v[8:9]
	v_pk_mov_b32 v[110:111], v[108:109], v[106:107] op_sel:[1,0]
	v_mov_b32_e32 v109, v107
	v_pk_add_f32 v[106:107], v[110:111], v[108:109]
	v_pk_mov_b32 v[108:109], v[104:105], v[96:97] op_sel:[1,0]
	v_mov_b32_e32 v105, v97
	v_pk_add_f32 v[96:97], v[108:109], v[104:105]
	v_pk_add_f32 v[106:107], v[106:107], v[106:107] op_sel_hi:[0,1]
	v_pk_add_f32 v[96:97], v[96:97], v[96:97] op_sel_hi:[0,1]
	v_mul_f32_e32 v96, v4, v4
	v_pk_fma_f32 v[104:105], v[4:5], v[4:5], v[96:97] op_sel_hi:[1,1,0]
	v_mul_f32_e32 v96, v6, v6
	v_pk_fma_f32 v[108:109], v[6:7], v[6:7], v[96:97] op_sel_hi:[1,1,0]
	v_mul_f32_e32 v104, v0, v0
	v_mul_f32_e32 v108, v1, v1
	v_mul_f32_e32 v106, v2, v2
	v_mul_f32_e32 v96, v3, v3
	v_pk_add_f32 v[104:105], v[104:105], v[108:109]
	v_pk_add_f32 v[96:97], v[106:107], v[96:97]
	s_waitcnt vmcnt(15)
	v_pk_add_f32 v[78:79], v[78:79], 1.0 op_sel_hi:[1,0]
	v_pk_add_f32 v[96:97], v[104:105], v[96:97]
	v_pk_add_f32 v[76:77], v[76:77], 1.0 op_sel_hi:[1,0]
	v_add_f32_e32 v87, v96, v97
	ds_bpermute_b32 v89, v81, v87
	s_and_b64 s[0:1], exec, vcc
	s_or_b64 s[10:11], s[0:1], s[10:11]
	v_readlane_b32 s0, v255, 24
	v_readlane_b32 s1, v255, 25
	s_waitcnt lgkmcnt(0)
	v_add_f32_e32 v87, v87, v89
	ds_bpermute_b32 v89, v98, v87
	v_lshl_add_u64 v[94:95], v[94:95], 0, s[80:81]
	s_waitcnt lgkmcnt(0)
	v_add_f32_e32 v87, v87, v89
	ds_bpermute_b32 v89, v99, v87
	s_waitcnt lgkmcnt(0)
	v_add_f32_e32 v87, v87, v89
	ds_bpermute_b32 v89, v100, v87
	s_waitcnt lgkmcnt(0)
	v_add_f32_e32 v87, v87, v89
	ds_bpermute_b32 v89, v101, v87
	s_waitcnt lgkmcnt(0)
	v_add_f32_e32 v87, v87, v89
	ds_bpermute_b32 v89, v102, v87
	s_waitcnt lgkmcnt(0)
	v_add_f32_e32 v87, v87, v89
	v_fmamk_f32 v87, v87, 0x3a800000, v193
	v_rsq_f32_e32 v96, v87
	s_nop 0
	v_pk_mul_f32 v[14:15], v[14:15], v[96:97] op_sel_hi:[1,0]
	v_pk_mul_f32 v[12:13], v[12:13], v[96:97] op_sel_hi:[1,0]
	s_waitcnt vmcnt(13)
	v_pk_mul_f32 v[14:15], v[70:71], v[14:15]
	v_pk_mul_f32 v[12:13], v[68:69], v[12:13]
	v_pk_mul_f32 v[8:9], v[8:9], v[96:97] op_sel_hi:[1,0]
	v_pk_fma_f32 v[14:15], v[78:79], v[14:15], v[66:67]
	v_pk_fma_f32 v[12:13], v[76:77], v[12:13], v[64:65]
	v_pk_mul_f32 v[10:11], v[10:11], v[96:97] op_sel_hi:[1,0]
	s_waitcnt vmcnt(12)
	v_pk_mul_f32 v[8:9], v[56:57], v[8:9]
	v_cvt_pk_bf16_f32 v12, v12, v13
	v_cvt_pk_bf16_f32 v13, v14, v15
	s_waitcnt vmcnt(5)
	v_pk_add_f32 v[14:15], v[72:73], 1.0 op_sel_hi:[1,0]
	global_store_dwordx2 v[84:85], v[12:13], off
	v_pk_mul_f32 v[10:11], v[58:59], v[10:11]
	v_pk_add_f32 v[12:13], v[74:75], 1.0 op_sel_hi:[1,0]
	v_pk_fma_f32 v[8:9], v[14:15], v[8:9], v[60:61]
	v_pk_fma_f32 v[10:11], v[12:13], v[10:11], v[62:63]
	v_cvt_pk_bf16_f32 v8, v8, v9
	v_pk_mul_f32 v[6:7], v[6:7], v[96:97] op_sel_hi:[1,0]
	v_cvt_pk_bf16_f32 v9, v10, v11
	v_pk_mul_f32 v[4:5], v[4:5], v[96:97] op_sel_hi:[1,0]
	global_store_dwordx2 v[84:85], v[8:9], off offset:512
	v_pk_mul_f32 v[4:5], v[48:49], v[4:5]
	v_pk_mul_f32 v[6:7], v[50:51], v[6:7]
	v_pk_add_f32 v[8:9], v[54:55], 1.0 op_sel_hi:[1,0]
	v_pk_add_f32 v[10:11], v[52:53], 1.0 op_sel_hi:[1,0]
	v_pk_fma_f32 v[6:7], v[8:9], v[6:7], v[46:47]
	v_pk_fma_f32 v[4:5], v[10:11], v[4:5], v[44:45]
	v_pk_mul_f32 v[0:1], v[0:1], v[96:97] op_sel_hi:[1,0]
	v_cvt_pk_bf16_f32 v4, v4, v5
	v_cvt_pk_bf16_f32 v5, v6, v7
	v_pk_mul_f32 v[2:3], v[2:3], v[96:97] op_sel_hi:[1,0]
	v_pk_mul_f32 v[0:1], v[36:37], v[0:1]
	v_pk_add_f32 v[6:7], v[40:41], 1.0 op_sel_hi:[1,0]
	global_store_dwordx2 v[84:85], v[4:5], off offset:1024
	v_pk_mul_f32 v[2:3], v[38:39], v[2:3]
	v_pk_add_f32 v[4:5], v[42:43], 1.0 op_sel_hi:[1,0]
	s_waitcnt vmcnt(7)
	v_pk_fma_f32 v[0:1], v[6:7], v[0:1], v[32:33]
	v_pk_fma_f32 v[2:3], v[4:5], v[2:3], v[34:35]
	v_cvt_pk_bf16_f32 v0, v0, v1
	s_nop 0
	v_cvt_pk_bf16_f32 v1, v2, v3
	global_store_dwordx2 v[84:85], v[0:1], off offset:1536
	s_waitcnt vmcnt(4)
	v_mov_b64_e32 v[12:13], v[16:17]
	v_mov_b64_e32 v[8:9], v[20:21]
	v_mov_b64_e32 v[4:5], v[24:25]
	v_mov_b64_e32 v[0:1], v[28:29]
	v_lshl_add_u64 v[84:85], v[84:85], 0, s[0:1]
	v_mov_b32_e32 v96, v103
	v_mov_b64_e32 v[14:15], v[18:19]
	v_mov_b64_e32 v[10:11], v[22:23]
	v_mov_b64_e32 v[6:7], v[26:27]
	v_mov_b64_e32 v[2:3], v[30:31]
	s_andn2_b64 exec, exec, s[10:11]
	s_cbranch_execz .LBB0_180

; __device__ __forceinline__ int fresh_tid() { int t = threadIdx.x; asm volatile("" : "+v"(t)); return t; }
; #define NORM_LOADX(dst, r_) do { const int r__ = (r_); const float* xr_ = r__ < NLAT ? xlat + (size_t)r__ * DM : xctx + (size_t)(r__ - NLAT) * DM; \
;         _Pragma("unroll") for (int j = 0; j < 4; ++j) dst[j] = *(const f32x4*)(xr_ + 4 * lane + 256 * j); } while (0)
; __device__ __forceinline__ void norm_phase(const float* xlat, const float* xctx, const float* gvec, const float* mod, int sh_off, int sc_off, bf16_t* H, int nrows,
;                                            const float* part, const float* pgate, float* xctx_out, int row_lo) {
;     const int tid = fresh_tid(), lane = tid & 63, gw = row_lo + blockIdx.x * 8 + (tid >> 6), NGW = gridDim.x * 8;
;     f32x4 vn[4];
;     ...
;     if (gw < nrows) NORM_LOADX(vn, gw);
;     for (int row = gw; row < nrows; row += NGW) {
;         const int bb = row < NLAT ? row >> 11 : 8;
;         f32x4 v[4]; float ss = 0.f;
; #pragma unroll
;         for (int j = 0; j < 4; ++j) v[j] = vn[j];
;         if (row + NGW < nrows) NORM_LOADX(vn, row + NGW);
;         const float* mp = mod + bb * 6144;
;         f32x4 gg[4], sc[4], sh[4];
; #pragma unroll
;         for (int j = 0; j < 4; ++j) { const int col = 4 * lane + 256 * j; gg[j] = *(const f32x4*)(gvec + col); sc[j] = *(const f32x4*)(mp + sc_off + col); sh[j] = *(const f32x4*)(mp + sh_off + col); }
.LBB0_1134:
	s_or_b64 exec, exec, s[0:1]
	v_readlane_b32 s0, v255, 34
	v_readlane_b32 s1, v255, 35
	s_andn2_b64 vcc, exec, s[0:1]
	s_waitcnt lgkmcnt(0)
	v_cndmask_b32_e64 v0, 0, 1, s[0:1]
	v_cmp_ne_u32_e64 s[4:5], 1, v0
	s_barrier
	s_cbranch_vccnz .LBB0_1195
	s_and_b64 s[0:1], s[34:35], exec
	s_cselect_b32 s12, 0x4000, 0
	v_mov_b32_e32 v19, v192
	v_readlane_b32 s0, v253, 0
	s_add_i32 s0, s12, s0
	v_ashrrev_i32_e32 v18, 6, v19
	v_add_u32_e32 v16, s0, v18
	v_cmp_gt_i32_e32 vcc, s30, v16
	s_and_saveexec_b64 s[6:7], vcc
	s_cbranch_execz .LBB0_1142
	s_movk_i32 s0, 0x4000
	v_readlane_b32 s52, v252, 0
	v_cmp_gt_i32_e32 vcc, s0, v16
	v_readlane_b32 s0, v255, 30
	v_readlane_b32 s55, v252, 3
	v_add_u32_e32 v0, 0xffffc000, v16
	v_ashrrev_i32_e32 v17, 31, v16
	v_mov_b32_e32 v2, s0
	v_readlane_b32 s54, v252, 2
	v_mov_b32_e32 v3, s55
	v_readlane_b32 s0, v255, 31
	v_cndmask_b32_e32 v1, 0, v17, vcc
	v_cndmask_b32_e32 v0, v0, v16, vcc
	v_cndmask_b32_e32 v3, v2, v3, vcc
	v_mov_b32_e32 v2, s0
	v_mov_b32_e32 v4, s54
	v_cndmask_b32_e32 v2, v2, v4, vcc
	v_lshlrev_b64 v[0:1], 12, v[0:1]
	v_lshl_add_u64 v[0:1], v[2:3], 0, v[0:1]
	v_lshlrev_b32_e32 v2, 2, v19
	v_and_b32_e32 v80, 0xfc, v2
	v_lshlrev_b32_e32 v160, 2, v80
	v_lshl_add_u64 v[0:1], v[0:1], 0, v[160:161]
	global_load_dwordx4 v[12:15], v[0:1], off
	global_load_dwordx4 v[8:11], v[0:1], off offset:1024
	global_load_dwordx4 v[4:7], v[0:1], off offset:2048
	s_nop 0
	global_load_dwordx4 v[0:3], v[0:1], off offset:3072
	v_readlane_b32 s0, v255, 26
	v_readlane_b32 s53, v252, 1
	v_readlane_b32 s56, v252, 4
	v_readlane_b32 s57, v252, 5
	v_readlane_b32 s58, v252, 6
	v_readlane_b32 s59, v252, 7
	v_readlane_b32 s1, v255, 27
	v_readlane_b32 s10, v255, 38
	s_and_b64 s[0:1], s[0:1], exec
	v_readlane_b32 s11, v255, 39
	v_readlane_b32 s52, v252, 16
	s_cselect_b32 s13, s23, 0
	s_cselect_b32 s15, s22, 0
	s_lshl_b64 s[10:11], s[10:11], 2
	v_readlane_b32 s66, v252, 30
	v_readlane_b32 s67, v252, 31
	s_add_u32 s24, s66, s10
	s_addc_u32 s25, s67, s11
	s_add_u32 s10, s15, 0x800000
	s_addc_u32 s11, s13, 0
	s_add_u32 s46, s15, 0x1000000
	s_mov_b64 s[0:1], 0x32000
	v_lshl_add_u64 v[26:27], s[48:49], 0, v[160:161]
	s_addc_u32 s47, s13, 0
	v_and_b32_e32 v19, 63, v19
	v_lshlrev_b64 v[16:17], 11, v[16:17]
	v_lshl_add_u64 v[90:91], v[26:27], 0, s[0:1]
	s_add_u32 s50, s15, 0x1800000
	v_readlane_b32 s0, v255, 13
	v_readlane_b32 s1, v255, 14
	v_or_b32_e32 v20, 0x100, v80
	v_or_b32_e32 v22, 0x200, v80
	v_or_b32_e32 v24, 0x300, v80
	v_lshl_or_b32 v16, v19, 3, v16
	s_addc_u32 s51, s13, 0
	s_add_i32 s0, s0, s12
	s_add_i32 s1, s1, s12
	v_lshl_add_u64 v[82:83], s[18:19], 0, v[16:17]
	v_lshlrev_b32_e32 v84, 2, v20
	v_lshlrev_b32_e32 v86, 2, v22
	v_lshlrev_b32_e32 v88, 2, v24
	v_add_u32_e32 v96, s0, v18
	v_add_u32_e32 v94, s1, v18
	s_mov_b64 s[8:9], 0
	v_lshl_add_u64 v[92:93], s[24:25], 0, v[160:161]
	v_lshlrev_b32_e32 v160, 2, v80
	v_ashrrev_i32_e32 v95, 31, v94
	v_readlane_b32 s53, v252, 17
	v_readlane_b32 s54, v252, 18
	v_readlane_b32 s55, v252, 19
	v_readlane_b32 s56, v252, 20
	v_readlane_b32 s57, v252, 21
	v_readlane_b32 s58, v252, 22
	v_readlane_b32 s59, v252, 23
	v_readlane_b32 s60, v252, 24
	v_readlane_b32 s61, v252, 25
	v_readlane_b32 s62, v252, 26
	v_readlane_b32 s63, v252, 27
	v_readlane_b32 s64, v252, 28
	v_readlane_b32 s65, v252, 29
	s_nop 0
	s_nop 0
	s_nop 0
	s_nop 0
	s_nop 0
	s_nop 0
	s_nop 0
	s_nop 0
	s_nop 0
	s_nop 0
	s_nop 0
	s_nop 0
	s_branch .LBB0_1138
; __device__ __forceinline__ u32x2 pack4(f32x4 v) { u32x2 w; w.x = cvt_pk_bf16(v[0], v[1]); w.y = cvt_pk_bf16(v[2], v[3]); return w; }
; __device__ __forceinline__ float wave_sum(float v) {
; #pragma unroll
;     for (int o = 1; o < 64; o <<= 1) v += __shfl_xor(v, o);
;     return v;
; __device__ __forceinline__ void norm_phase(const float* xlat, const float* xctx, const float* gvec, const float* mod, int sh_off, int sc_off, bf16_t* H, int nrows,
;                                            const float* part, const float* pgate, float* xctx_out, int row_lo) {
;     ...
;         for (int j = 0; j < 4; ++j) ss += (v[j][0] * v[j][0] + v[j][1] * v[j][1]) + (v[j][2] * v[j][2] + v[j][3] * v[j][3]);
;         const float rstd = __builtin_amdgcn_rsqf(wave_sum(ss) * (1.f / DM) + EPSV);
; #pragma unroll
;         for (int j = 0; j < 4; ++j) {
;             const int col = 4 * lane + 256 * j;
;             const f32x4 y = (v[j] * rstd) * gg[j];
;             const f32x4 hv = y * (sc[j] + 1.f) + sh[j];
;             *(u32x2*)(H + (size_t)row * DM + col) = pack4(hv);
;         }
.LBB0_1137:
	s_or_b64 exec, exec, s[0:1]
	s_waitcnt vmcnt(12)
	v_pk_mul_f32 v[100:101], v[14:15], v[14:15]
	v_pk_mul_f32 v[102:103], v[12:13], v[12:13]
	v_pk_mul_f32 v[96:97], v[10:11], v[10:11]
	v_pk_mul_f32 v[98:99], v[8:9], v[8:9]
	v_pk_mov_b32 v[104:105], v[102:103], v[100:101] op_sel:[1,0]
	v_mov_b32_e32 v103, v101
	v_pk_add_f32 v[100:101], v[104:105], v[102:103]
	v_pk_mov_b32 v[102:103], v[98:99], v[96:97] op_sel:[1,0]
	v_mov_b32_e32 v99, v97
	v_pk_add_f32 v[96:97], v[102:103], v[98:99]
	v_pk_add_f32 v[100:101], v[100:101], v[100:101] op_sel_hi:[0,1]
	v_pk_add_f32 v[96:97], v[96:97], v[96:97] op_sel_hi:[0,1]
	v_mul_f32_e32 v96, v4, v4
	v_pk_fma_f32 v[98:99], v[4:5], v[4:5], v[96:97] op_sel_hi:[1,1,0]
	v_mul_f32_e32 v96, v6, v6
	v_pk_fma_f32 v[102:103], v[6:7], v[6:7], v[96:97] op_sel_hi:[1,1,0]
	v_mul_f32_e32 v98, v0, v0
	v_mul_f32_e32 v102, v1, v1
	v_mul_f32_e32 v100, v2, v2
	v_mul_f32_e32 v96, v3, v3
	v_pk_add_f32 v[98:99], v[98:99], v[102:103]
	v_pk_add_f32 v[96:97], v[100:101], v[96:97]
	s_waitcnt vmcnt(11)
	v_pk_add_f32 v[78:79], v[78:79], 1.0 op_sel_hi:[1,0]
	v_pk_add_f32 v[96:97], v[98:99], v[96:97]
	v_pk_add_f32 v[76:77], v[76:77], 1.0 op_sel_hi:[1,0]
	v_add_f32_e32 v85, v96, v97
	ds_bpermute_b32 v87, v209, v85
	s_and_b64 s[0:1], exec, vcc
	s_or_b64 s[8:9], s[0:1], s[8:9]
	v_readlane_b32 s0, v255, 24
	v_readlane_b32 s1, v255, 25
	s_waitcnt lgkmcnt(0)
	v_add_f32_e32 v85, v85, v87
	ds_bpermute_b32 v87, v210, v85
	v_lshl_add_u64 v[94:95], v[94:95], 0, s[80:81]
	s_waitcnt lgkmcnt(0)
	v_add_f32_e32 v85, v85, v87
	ds_bpermute_b32 v87, v211, v85
	s_waitcnt lgkmcnt(0)
	v_add_f32_e32 v85, v85, v87
	ds_bpermute_b32 v87, v212, v85
	s_waitcnt lgkmcnt(0)
	v_add_f32_e32 v85, v85, v87
	ds_bpermute_b32 v87, v213, v85
	s_waitcnt lgkmcnt(0)
	v_add_f32_e32 v85, v85, v87
	ds_bpermute_b32 v87, v214, v85
	s_waitcnt lgkmcnt(0)
	v_add_f32_e32 v85, v85, v87
	v_fmamk_f32 v85, v85, 0x3a800000, v193
	v_rsq_f32_e32 v96, v85
	s_nop 0
	v_pk_mul_f32 v[14:15], v[14:15], v[96:97] op_sel_hi:[1,0]
	v_pk_mul_f32 v[12:13], v[12:13], v[96:97] op_sel_hi:[1,0]
	s_waitcnt vmcnt(9)
	v_pk_mul_f32 v[14:15], v[74:75], v[14:15]
	v_pk_mul_f32 v[12:13], v[72:73], v[12:13]
	v_pk_mul_f32 v[8:9], v[8:9], v[96:97] op_sel_hi:[1,0]
	v_pk_fma_f32 v[14:15], v[78:79], v[14:15], v[70:71]
	v_pk_fma_f32 v[12:13], v[76:77], v[12:13], v[68:69]
	v_pk_mul_f32 v[10:11], v[10:11], v[96:97] op_sel_hi:[1,0]
	s_waitcnt vmcnt(8)
	v_pk_mul_f32 v[8:9], v[60:61], v[8:9]
	v_cvt_pk_bf16_f32 v12, v12, v13
	v_cvt_pk_bf16_f32 v13, v14, v15
	s_waitcnt vmcnt(7)
	v_pk_add_f32 v[14:15], v[64:65], 1.0 op_sel_hi:[1,0]
	global_store_dwordx2 v[82:83], v[12:13], off
	v_pk_mul_f32 v[10:11], v[62:63], v[10:11]
	v_pk_add_f32 v[12:13], v[66:67], 1.0 op_sel_hi:[1,0]
	s_waitcnt vmcnt(7)
	v_pk_fma_f32 v[8:9], v[14:15], v[8:9], v[56:57]
	v_pk_fma_f32 v[10:11], v[12:13], v[10:11], v[58:59]
	v_cvt_pk_bf16_f32 v8, v8, v9
	v_pk_mul_f32 v[6:7], v[6:7], v[96:97] op_sel_hi:[1,0]
	v_cvt_pk_bf16_f32 v9, v10, v11
	v_pk_mul_f32 v[4:5], v[4:5], v[96:97] op_sel_hi:[1,0]
	global_store_dwordx2 v[82:83], v[8:9], off offset:512
	s_waitcnt vmcnt(5)
	v_pk_mul_f32 v[4:5], v[52:53], v[4:5]
	v_pk_mul_f32 v[6:7], v[54:55], v[6:7]
	v_pk_add_f32 v[8:9], v[50:51], 1.0 op_sel_hi:[1,0]
	v_pk_add_f32 v[10:11], v[48:49], 1.0 op_sel_hi:[1,0]
	v_pk_fma_f32 v[6:7], v[8:9], v[6:7], v[46:47]
	v_pk_fma_f32 v[4:5], v[10:11], v[4:5], v[44:45]
	v_pk_mul_f32 v[0:1], v[0:1], v[96:97] op_sel_hi:[1,0]
	v_cvt_pk_bf16_f32 v4, v4, v5
	v_cvt_pk_bf16_f32 v5, v6, v7
	v_pk_mul_f32 v[2:3], v[2:3], v[96:97] op_sel_hi:[1,0]
	s_waitcnt vmcnt(4)
	v_pk_mul_f32 v[0:1], v[36:37], v[0:1]
	s_waitcnt vmcnt(3)
	v_pk_add_f32 v[6:7], v[40:41], 1.0 op_sel_hi:[1,0]
	global_store_dwordx2 v[82:83], v[4:5], off offset:1024
	v_pk_mul_f32 v[2:3], v[38:39], v[2:3]
	v_pk_add_f32 v[4:5], v[42:43], 1.0 op_sel_hi:[1,0]
	s_waitcnt vmcnt(3)
	v_pk_fma_f32 v[0:1], v[6:7], v[0:1], v[32:33]
	v_pk_fma_f32 v[2:3], v[4:5], v[2:3], v[34:35]
	v_cvt_pk_bf16_f32 v0, v0, v1
	v_mov_b64_e32 v[12:13], v[16:17]
	v_cvt_pk_bf16_f32 v1, v2, v3
	global_store_dwordx2 v[82:83], v[0:1], off offset:1536
	v_mov_b64_e32 v[8:9], v[20:21]
	v_mov_b64_e32 v[4:5], v[24:25]
	v_mov_b64_e32 v[0:1], v[28:29]
	v_lshl_add_u64 v[82:83], v[82:83], 0, s[0:1]
	v_mov_b32_e32 v96, v81
	v_mov_b64_e32 v[14:15], v[18:19]
	v_mov_b64_e32 v[10:11], v[22:23]
	v_mov_b64_e32 v[6:7], v[26:27]
	v_mov_b64_e32 v[2:3], v[30:31]
	s_andn2_b64 exec, exec, s[8:9]
	s_cbranch_execz .LBB0_1142
